# first down GEMM (L0) latent residual epilogue rewritten: f32 source loads 6 groups deep instead of serialised round trips
# baseline (speedup 1.0000x reference)
; __device__ __forceinline__ unsigned cvt_pk_bf16(float lo, float hi) { unsigned r; asm("v_cvt_pk_bf16_f32 %0, %1, %2" : "=v"(r) : "v"(lo), "v"(hi)); return r; }
;     __device__ __forceinline__ void operator()(const Acc& acc, const Unit& u, int wr, int wc, int fr, int fq) const {
;     ...
;         const int r0 = wr * 64 + fr, col0 = u.pn * 256 + wc * 32 + 8 * fq; const float* gp = gate + (size_t)mb * 9216 + col0;
;         f32x4 gv[2][2];
; #pragma unroll
;         for (int bj = 0; bj < 2; ++bj)
; #pragma unroll
;             for (int n = 0; n < 2; ++n) gv[bj][n] = *(const f32x4*)(gp + bj * 128 + n * 4) * f;
; #pragma unroll
;         for (int ai = 0; ai < 2; ++ai)
; #pragma unroll
;             for (int m = 0; m < 4; ++m) { const size_t off = (size_t)(r0 + ai * 128 + m * 16) * D + col0;
; #pragma unroll
;                 for (int bj = 0; bj < 2; ++bj) { const size_t o2 = off + bj * 128; f32x4 s0, s1;
;                     if (SRC32) { s0 = *(const f32x4*)(sp32 + o2); s1 = *(const f32x4*)(sp32 + o2 + 4); }
;                     else { const u32x4 q = *(const u32x4*)(sp16 + o2); s0 = (f32x4){bf2f(q.x & 0xffffu), bf2f(q.x >> 16), bf2f(q.y & 0xffffu), bf2f(q.y >> 16)}; s1 = (f32x4){bf2f(q.z & 0xffffu), bf2f(q.z >> 16), bf2f(q.w & 0xffffu), bf2f(q.w >> 16)}; }
;                     const f32x4 v0 = s0 + gv[bj][0] * acc[ai][bj][m][0], v1 = s1 + gv[bj][1] * acc[ai][bj][m][1];
;                     if (DST32) { *(f32x4*)(dp32 + o2) = v0; *(f32x4*)(dp32 + o2 + 4) = v1; }
;                     else { u32x4 w; w.x = cvt_pk_bf16(v0.x, v0.y); w.y = cvt_pk_bf16(v0.z, v0.w); w.z = cvt_pk_bf16(v1.x, v1.y); w.w = cvt_pk_bf16(v1.z, v1.w); *(u32x4*)(dp16 + o2) = w; } } }
.LBB0_357:
	s_ashr_i32 s0, s28, 4
	s_ashr_i32 s29, s28, 31
	s_mul_hi_i32 s33, s0, 0x9000
	s_mul_i32 s0, s0, 0x9000
	s_add_u32 s34, s52, s0
	s_addc_u32 s35, s53, s33
	v_lshl_or_b32 v204, s69, 8, v185
	v_lshlrev_b32_e32 v182, 2, v204
	global_load_dwordx4 v[174:177], v182, s[34:35]
	global_load_dwordx4 v[178:181], v182, s[34:35] offset:16
	global_load_dwordx4 v[188:191], v182, s[34:35] offset:512
	global_load_dwordx4 v[192:195], v182, s[34:35] offset:528
	s_lshl_b64 s[34:35], s[28:29], 20
	s_add_u32 s38, s36, s34
	s_addc_u32 s39, s37, s35
	s_lshl_b64 s[28:29], s[28:29], 19
	s_add_u32 s28, s86, s28
	s_addc_u32 s29, s87, s29
	v_add_lshl_u32 v183, v150, v204, 2
	global_load_dwordx4 v[196:199], v183, s[38:39]
	global_load_dwordx4 v[200:203], v183, s[38:39] offset:16
	v_add_lshl_u32 v182, v150, v204, 2
	global_load_dwordx4 v[208:211], v182, s[38:39] offset:512
	global_load_dwordx4 v[212:215], v182, s[38:39] offset:528
	v_add_lshl_u32 v183, v152, v204, 2
	global_load_dwordx4 v[216:219], v183, s[38:39]
	global_load_dwordx4 v[220:223], v183, s[38:39] offset:16
	v_add_lshl_u32 v182, v152, v204, 2
	global_load_dwordx4 v[224:227], v182, s[38:39] offset:512
	global_load_dwordx4 v[228:231], v182, s[38:39] offset:528
	v_add_lshl_u32 v183, v154, v204, 2
	global_load_dwordx4 v[232:235], v183, s[38:39]
	global_load_dwordx4 v[236:239], v183, s[38:39] offset:16
	v_add_lshl_u32 v182, v154, v204, 2
	global_load_dwordx4 v[240:243], v182, s[38:39] offset:512
	global_load_dwordx4 v[244:247], v182, s[38:39] offset:528
	s_waitcnt vmcnt(10)
	v_pk_mul_f32 v[174:175], v[174:175], 0.5 op_sel_hi:[1,0]
	v_pk_mul_f32 v[176:177], v[176:177], 0.5 op_sel_hi:[1,0]
	v_pk_mul_f32 v[178:179], v[178:179], 0.5 op_sel_hi:[1,0]
	v_pk_mul_f32 v[180:181], v[180:181], 0.5 op_sel_hi:[1,0]
	v_pk_mul_f32 v[188:189], v[188:189], 0.5 op_sel_hi:[1,0]
	v_pk_mul_f32 v[190:191], v[190:191], 0.5 op_sel_hi:[1,0]
	v_pk_mul_f32 v[192:193], v[192:193], 0.5 op_sel_hi:[1,0]
	v_pk_mul_f32 v[194:195], v[194:195], 0.5 op_sel_hi:[1,0]
	v_pk_fma_f32 v[124:125], v[124:125], v[174:175], v[196:197]
	v_pk_fma_f32 v[126:127], v[126:127], v[176:177], v[198:199]
	v_pk_fma_f32 v[120:121], v[120:121], v[178:179], v[200:201]
	v_pk_fma_f32 v[122:123], v[122:123], v[180:181], v[202:203]
	v_cvt_pk_bf16_f32 v124, v124, v125
	v_cvt_pk_bf16_f32 v125, v126, v127
	v_cvt_pk_bf16_f32 v126, v120, v121
	v_cvt_pk_bf16_f32 v127, v122, v123
	v_add_lshl_u32 v183, v156, v204, 2
	global_load_dwordx4 v[196:199], v183, s[38:39]
	global_load_dwordx4 v[200:203], v183, s[38:39] offset:16
	s_waitcnt vmcnt(10)
	v_pk_fma_f32 v[116:117], v[116:117], v[188:189], v[208:209]
	v_pk_fma_f32 v[118:119], v[118:119], v[190:191], v[210:211]
	v_pk_fma_f32 v[112:113], v[112:113], v[192:193], v[212:213]
	v_pk_fma_f32 v[114:115], v[114:115], v[194:195], v[214:215]
	v_cvt_pk_bf16_f32 v116, v116, v117
	v_cvt_pk_bf16_f32 v117, v118, v119
	v_cvt_pk_bf16_f32 v118, v112, v113
	v_cvt_pk_bf16_f32 v119, v114, v115
	v_add_lshl_u32 v182, v156, v204, 2
	global_load_dwordx4 v[208:211], v182, s[38:39] offset:512
	global_load_dwordx4 v[212:215], v182, s[38:39] offset:528
	s_waitcnt vmcnt(10)
	v_pk_fma_f32 v[108:109], v[108:109], v[174:175], v[216:217]
	v_pk_fma_f32 v[110:111], v[110:111], v[176:177], v[218:219]
	v_pk_fma_f32 v[104:105], v[104:105], v[178:179], v[220:221]
	v_pk_fma_f32 v[106:107], v[106:107], v[180:181], v[222:223]
	v_cvt_pk_bf16_f32 v108, v108, v109
	v_cvt_pk_bf16_f32 v109, v110, v111
	v_cvt_pk_bf16_f32 v110, v104, v105
	v_cvt_pk_bf16_f32 v111, v106, v107
	v_add_lshl_u32 v183, v158, v204, 2
	global_load_dwordx4 v[216:219], v183, s[38:39]
	global_load_dwordx4 v[220:223], v183, s[38:39] offset:16
	s_waitcnt vmcnt(10)
	v_pk_fma_f32 v[100:101], v[100:101], v[188:189], v[224:225]
	v_pk_fma_f32 v[102:103], v[102:103], v[190:191], v[226:227]
	v_pk_fma_f32 v[96:97], v[96:97], v[192:193], v[228:229]
	v_pk_fma_f32 v[98:99], v[98:99], v[194:195], v[230:231]
	v_cvt_pk_bf16_f32 v100, v100, v101
	v_cvt_pk_bf16_f32 v101, v102, v103
	v_cvt_pk_bf16_f32 v102, v96, v97
	v_cvt_pk_bf16_f32 v103, v98, v99
	v_add_lshl_u32 v182, v158, v204, 2
	global_load_dwordx4 v[224:227], v182, s[38:39] offset:512
	global_load_dwordx4 v[228:231], v182, s[38:39] offset:528
	s_waitcnt vmcnt(10)
	v_pk_fma_f32 v[92:93], v[92:93], v[174:175], v[232:233]
	v_pk_fma_f32 v[94:95], v[94:95], v[176:177], v[234:235]
	v_pk_fma_f32 v[88:89], v[88:89], v[178:179], v[236:237]
	v_pk_fma_f32 v[90:91], v[90:91], v[180:181], v[238:239]
	v_cvt_pk_bf16_f32 v92, v92, v93
	v_cvt_pk_bf16_f32 v93, v94, v95
	v_cvt_pk_bf16_f32 v94, v88, v89
	v_cvt_pk_bf16_f32 v95, v90, v91
	v_add_lshl_u32 v183, v160, v204, 2
	global_load_dwordx4 v[232:235], v183, s[38:39]
	global_load_dwordx4 v[236:239], v183, s[38:39] offset:16
	s_waitcnt vmcnt(10)
	v_pk_fma_f32 v[84:85], v[84:85], v[188:189], v[240:241]
	v_pk_fma_f32 v[86:87], v[86:87], v[190:191], v[242:243]
	v_pk_fma_f32 v[80:81], v[80:81], v[192:193], v[244:245]
	v_pk_fma_f32 v[82:83], v[82:83], v[194:195], v[246:247]
	v_cvt_pk_bf16_f32 v84, v84, v85
	v_cvt_pk_bf16_f32 v85, v86, v87
	v_cvt_pk_bf16_f32 v86, v80, v81
	v_cvt_pk_bf16_f32 v87, v82, v83
	v_add_lshl_u32 v182, v160, v204, 2
	global_load_dwordx4 v[240:243], v182, s[38:39] offset:512
	global_load_dwordx4 v[244:247], v182, s[38:39] offset:528
	s_waitcnt vmcnt(10)
; __device__ __forceinline__ unsigned cvt_pk_bf16(float lo, float hi) { unsigned r; asm("v_cvt_pk_bf16_f32 %0, %1, %2" : "=v"(r) : "v"(lo), "v"(hi)); return r; }
;     __device__ __forceinline__ void operator()(const Acc& acc, const Unit& u, int wr, int wc, int fr, int fq) const {
;     ...
;             for (int m = 0; m < 4; ++m) { const size_t off = (size_t)(r0 + ai * 128 + m * 16) * D + col0;
; #pragma unroll
;                 for (int bj = 0; bj < 2; ++bj) { const size_t o2 = off + bj * 128; f32x4 s0, s1;
;                     if (SRC32) { s0 = *(const f32x4*)(sp32 + o2); s1 = *(const f32x4*)(sp32 + o2 + 4); }
;                     else { const u32x4 q = *(const u32x4*)(sp16 + o2); s0 = (f32x4){bf2f(q.x & 0xffffu), bf2f(q.x >> 16), bf2f(q.y & 0xffffu), bf2f(q.y >> 16)}; s1 = (f32x4){bf2f(q.z & 0xffffu), bf2f(q.z >> 16), bf2f(q.w & 0xffffu), bf2f(q.w >> 16)}; }
;                     const f32x4 v0 = s0 + gv[bj][0] * acc[ai][bj][m][0], v1 = s1 + gv[bj][1] * acc[ai][bj][m][1];
;                     if (DST32) { *(f32x4*)(dp32 + o2) = v0; *(f32x4*)(dp32 + o2 + 4) = v1; }
;                     else { u32x4 w; w.x = cvt_pk_bf16(v0.x, v0.y); w.y = cvt_pk_bf16(v0.z, v0.w); w.z = cvt_pk_bf16(v1.x, v1.y); w.w = cvt_pk_bf16(v1.z, v1.w); *(u32x4*)(dp16 + o2) = w; } } }
	v_pk_fma_f32 v[76:77], v[76:77], v[174:175], v[196:197]
	v_pk_fma_f32 v[78:79], v[78:79], v[176:177], v[198:199]
	v_pk_fma_f32 v[72:73], v[72:73], v[178:179], v[200:201]
	v_pk_fma_f32 v[74:75], v[74:75], v[180:181], v[202:203]
	v_cvt_pk_bf16_f32 v76, v76, v77
	v_cvt_pk_bf16_f32 v77, v78, v79
	v_cvt_pk_bf16_f32 v78, v72, v73
	v_cvt_pk_bf16_f32 v79, v74, v75
	v_add_lshl_u32 v183, v162, v204, 2
	global_load_dwordx4 v[196:199], v183, s[38:39]
	global_load_dwordx4 v[200:203], v183, s[38:39] offset:16
	s_waitcnt vmcnt(10)
	v_pk_fma_f32 v[68:69], v[68:69], v[188:189], v[208:209]
	v_pk_fma_f32 v[70:71], v[70:71], v[190:191], v[210:211]
	v_pk_fma_f32 v[64:65], v[64:65], v[192:193], v[212:213]
	v_pk_fma_f32 v[66:67], v[66:67], v[194:195], v[214:215]
	v_cvt_pk_bf16_f32 v68, v68, v69
	v_cvt_pk_bf16_f32 v69, v70, v71
	v_cvt_pk_bf16_f32 v70, v64, v65
	v_cvt_pk_bf16_f32 v71, v66, v67
	v_add_lshl_u32 v182, v162, v204, 2
	global_load_dwordx4 v[208:211], v182, s[38:39] offset:512
	global_load_dwordx4 v[212:215], v182, s[38:39] offset:528
	s_waitcnt vmcnt(10)
	v_pk_fma_f32 v[60:61], v[60:61], v[174:175], v[216:217]
	v_pk_fma_f32 v[62:63], v[62:63], v[176:177], v[218:219]
	v_pk_fma_f32 v[56:57], v[56:57], v[178:179], v[220:221]
	v_pk_fma_f32 v[58:59], v[58:59], v[180:181], v[222:223]
	v_cvt_pk_bf16_f32 v60, v60, v61
	v_cvt_pk_bf16_f32 v61, v62, v63
	v_cvt_pk_bf16_f32 v62, v56, v57
	v_cvt_pk_bf16_f32 v63, v58, v59
	v_add_lshl_u32 v183, v164, v204, 2
	global_load_dwordx4 v[216:219], v183, s[38:39]
	global_load_dwordx4 v[220:223], v183, s[38:39] offset:16
	s_waitcnt vmcnt(10)
	v_pk_fma_f32 v[52:53], v[52:53], v[188:189], v[224:225]
	v_pk_fma_f32 v[54:55], v[54:55], v[190:191], v[226:227]
	v_pk_fma_f32 v[48:49], v[48:49], v[192:193], v[228:229]
	v_pk_fma_f32 v[50:51], v[50:51], v[194:195], v[230:231]
	v_cvt_pk_bf16_f32 v52, v52, v53
	v_cvt_pk_bf16_f32 v53, v54, v55
	v_cvt_pk_bf16_f32 v54, v48, v49
	v_cvt_pk_bf16_f32 v55, v50, v51
	v_add_lshl_u32 v182, v164, v204, 2
	global_load_dwordx4 v[224:227], v182, s[38:39] offset:512
	global_load_dwordx4 v[228:231], v182, s[38:39] offset:528
	s_waitcnt vmcnt(10)
	v_pk_fma_f32 v[44:45], v[44:45], v[174:175], v[232:233]
	v_pk_fma_f32 v[46:47], v[46:47], v[176:177], v[234:235]
	v_pk_fma_f32 v[40:41], v[40:41], v[178:179], v[236:237]
	v_pk_fma_f32 v[42:43], v[42:43], v[180:181], v[238:239]
	v_cvt_pk_bf16_f32 v44, v44, v45
	v_cvt_pk_bf16_f32 v45, v46, v47
	v_cvt_pk_bf16_f32 v46, v40, v41
	v_cvt_pk_bf16_f32 v47, v42, v43
	s_waitcnt vmcnt(8)
	v_pk_fma_f32 v[36:37], v[36:37], v[188:189], v[240:241]
	v_pk_fma_f32 v[38:39], v[38:39], v[190:191], v[242:243]
	v_pk_fma_f32 v[32:33], v[32:33], v[192:193], v[244:245]
	v_pk_fma_f32 v[34:35], v[34:35], v[194:195], v[246:247]
	v_cvt_pk_bf16_f32 v36, v36, v37
	v_cvt_pk_bf16_f32 v37, v38, v39
	v_cvt_pk_bf16_f32 v38, v32, v33
	v_cvt_pk_bf16_f32 v39, v34, v35
	s_waitcnt vmcnt(6)
	v_pk_fma_f32 v[28:29], v[28:29], v[174:175], v[196:197]
	v_pk_fma_f32 v[30:31], v[30:31], v[176:177], v[198:199]
	v_pk_fma_f32 v[24:25], v[24:25], v[178:179], v[200:201]
	v_pk_fma_f32 v[26:27], v[26:27], v[180:181], v[202:203]
	v_cvt_pk_bf16_f32 v28, v28, v29
	v_cvt_pk_bf16_f32 v29, v30, v31
	v_cvt_pk_bf16_f32 v30, v24, v25
	v_cvt_pk_bf16_f32 v31, v26, v27
	s_waitcnt vmcnt(4)
	v_pk_fma_f32 v[20:21], v[20:21], v[188:189], v[208:209]
	v_pk_fma_f32 v[22:23], v[22:23], v[190:191], v[210:211]
	v_pk_fma_f32 v[16:17], v[16:17], v[192:193], v[212:213]
	v_pk_fma_f32 v[18:19], v[18:19], v[194:195], v[214:215]
	v_cvt_pk_bf16_f32 v20, v20, v21
	v_cvt_pk_bf16_f32 v21, v22, v23
	v_cvt_pk_bf16_f32 v22, v16, v17
	v_cvt_pk_bf16_f32 v23, v18, v19
	s_waitcnt vmcnt(2)
	v_pk_fma_f32 v[12:13], v[12:13], v[174:175], v[216:217]
	v_pk_fma_f32 v[14:15], v[14:15], v[176:177], v[218:219]
	v_pk_fma_f32 v[8:9], v[8:9], v[178:179], v[220:221]
	v_pk_fma_f32 v[10:11], v[10:11], v[180:181], v[222:223]
	v_cvt_pk_bf16_f32 v12, v12, v13
	v_cvt_pk_bf16_f32 v13, v14, v15
	v_cvt_pk_bf16_f32 v14, v8, v9
	v_cvt_pk_bf16_f32 v15, v10, v11
	s_waitcnt vmcnt(0)
	v_pk_fma_f32 v[4:5], v[4:5], v[188:189], v[224:225]
	v_pk_fma_f32 v[6:7], v[6:7], v[190:191], v[226:227]
	v_pk_fma_f32 v[0:1], v[0:1], v[192:193], v[228:229]
	v_pk_fma_f32 v[2:3], v[2:3], v[194:195], v[230:231]
	v_cvt_pk_bf16_f32 v4, v4, v5
	v_cvt_pk_bf16_f32 v5, v6, v7
	v_cvt_pk_bf16_f32 v6, v0, v1
	v_cvt_pk_bf16_f32 v7, v2, v3
	v_add_lshl_u32 v182, v150, v204, 1
	global_store_dwordx4 v182, v[124:127], s[28:29]
	global_store_dwordx4 v182, v[116:119], s[28:29] offset:256
	v_add_lshl_u32 v183, v152, v204, 1
	global_store_dwordx4 v183, v[108:111], s[28:29]
	global_store_dwordx4 v183, v[100:103], s[28:29] offset:256
	v_add_lshl_u32 v182, v154, v204, 1
	global_store_dwordx4 v182, v[92:95], s[28:29]
	global_store_dwordx4 v182, v[84:87], s[28:29] offset:256
	v_add_lshl_u32 v183, v156, v204, 1
	global_store_dwordx4 v183, v[76:79], s[28:29]
	global_store_dwordx4 v183, v[68:71], s[28:29] offset:256
	v_add_lshl_u32 v182, v158, v204, 1
	global_store_dwordx4 v182, v[60:63], s[28:29]
	global_store_dwordx4 v182, v[52:55], s[28:29] offset:256
	v_add_lshl_u32 v183, v160, v204, 1
	global_store_dwordx4 v183, v[44:47], s[28:29]
	global_store_dwordx4 v183, v[36:39], s[28:29] offset:256
	v_add_lshl_u32 v182, v162, v204, 1
	global_store_dwordx4 v182, v[28:31], s[28:29]
	global_store_dwordx4 v182, v[20:23], s[28:29] offset:256
	v_add_lshl_u32 v183, v164, v204, 1
	global_store_dwordx4 v183, v[12:15], s[28:29]
	global_store_dwordx4 v183, v[4:7], s[28:29] offset:256
	s_andn2_b64 vcc, exec, s[4:5]
	s_mov_b64 s[4:5], -1
	s_cbranch_vccnz .LBB0_335
	s_branch .LBB0_362
